# tok0_mem phase 1: all 32 row loads + norm-weight loads issued together (was 8 serialized groups), on top of double-buffered score/accumulation loops
# speedup vs baseline: 1.0054x; 1.0054x over previous
; #define LAS __attribute__((address_space(3)))
; DI void tok0_mem(ldsp lds, const float* qm, const float* memb, const float* mnw, const float* Wkv, int hm, LAS float* out64, int tid, int wid, int lane) {
;     ...
;     for (int h2 = 0; h2 < 2; ++h2) {
;         const int j = tid + h2 * 512; const float* wr = Wkv + (size_t)j * 512 + hm * 64; float t = 0.f;
; #pragma unroll
;         for (int d4 = 0; d4 < 16; ++d4) { const float4 w4 = *(const float4*)(wr + d4 * 4); const f32x4 q4 = *(LAS f32x4*)(QS + d4 * 4); t += w4.x * q4[0] + w4.y * q4[1] + w4.z * q4[2] + w4.w * q4[3]; }
;         U[j] = t * mnw[j];
;     }
;     __syncthreads();
;     {
;         f32x4 u4[4];
; #pragma unroll
;         for (int q = 0; q < 4; ++q) u4[q] = *(LAS f32x4*)(U + q * 256 + lane * 4);
.LBB0_98:
	s_or_b64 exec, exec, s[22:23]
	s_lshl_b64 s[26:27], s[52:53], 20
	s_lshl_b32 s36, s37, 2
	v_readlane_b32 s0, v251, 47
	s_add_u32 s30, s0, s36
	v_readlane_b32 s0, v251, 48
	s_addc_u32 s31, s0, 0
	v_lshlrev_b64 v[2:3], 11, v[0:1]
	v_lshl_add_u64 v[2:3], s[30:31], 0, v[2:3]
	s_waitcnt lgkmcnt(0)
	s_barrier
	v_readlane_b32 s56, v254, 15
	v_readlane_b32 s60, v254, 19
	v_readlane_b32 s61, v254, 20
	v_lshl_add_u64 v[92:93], v[84:85], 0, s[26:27]
	s_mov_b32 s0, -4
	v_lshl_add_u64 v[90:91], v[0:1], 2, s[60:61]
	v_readlane_b32 s57, v254, 16
	v_readlane_b32 s58, v254, 17
	v_readlane_b32 s59, v254, 18
	v_readlane_b32 s62, v254, 21
	v_readlane_b32 s63, v254, 22
	v_readlane_b32 s64, v254, 23
	v_readlane_b32 s65, v254, 24
	v_readlane_b32 s66, v254, 25
	v_readlane_b32 s67, v254, 26
	v_readlane_b32 s68, v254, 27
	v_readlane_b32 s69, v254, 28
	v_readlane_b32 s70, v254, 29
	v_readlane_b32 s71, v254, 30
	v_lshl_add_u64 v[246:247], s[30:31], 0, v[78:79]
	s_mov_b32 s30, s15
	global_load_dwordx4 v[158:161], v[2:3], off
	global_load_dwordx4 v[18:21], v[246:247], off
	global_load_dwordx4 v[162:165], v[2:3], off offset:16
	global_load_dwordx4 v[22:25], v[246:247], off offset:16
	global_load_dwordx4 v[166:169], v[2:3], off offset:32
	global_load_dwordx4 v[26:29], v[246:247], off offset:32
	global_load_dwordx4 v[170:173], v[2:3], off offset:48
	global_load_dwordx4 v[34:37], v[246:247], off offset:48
	global_load_dwordx4 v[174:177], v[2:3], off offset:64
	global_load_dwordx4 v[38:41], v[246:247], off offset:64
	global_load_dwordx4 v[178:181], v[2:3], off offset:80
	global_load_dwordx4 v[42:45], v[246:247], off offset:80
	global_load_dwordx4 v[182:185], v[2:3], off offset:96
	global_load_dwordx4 v[46:49], v[246:247], off offset:96
	global_load_dwordx4 v[186:189], v[2:3], off offset:112
	global_load_dwordx4 v[50:53], v[246:247], off offset:112
	global_load_dwordx4 v[190:193], v[2:3], off offset:128
	global_load_dwordx4 v[54:57], v[246:247], off offset:128
	global_load_dwordx4 v[194:197], v[2:3], off offset:144
	global_load_dwordx4 v[58:61], v[246:247], off offset:144
	global_load_dwordx4 v[198:201], v[2:3], off offset:160
	global_load_dwordx4 v[62:65], v[246:247], off offset:160
	global_load_dwordx4 v[202:205], v[2:3], off offset:176
	global_load_dwordx4 v[66:69], v[246:247], off offset:176
	global_load_dwordx4 v[206:209], v[2:3], off offset:192
	global_load_dwordx4 v[70:73], v[246:247], off offset:192
	global_load_dwordx4 v[210:213], v[2:3], off offset:208
	global_load_dwordx4 v[74:77], v[246:247], off offset:208
	global_load_dwordx4 v[214:217], v[2:3], off offset:224
	global_load_dwordx4 v[120:123], v[246:247], off offset:224
	global_load_dwordx4 v[218:221], v[2:3], off offset:240
	global_load_dwordx4 v[124:127], v[246:247], off offset:240
	global_load_dword v10, v[90:91], off
	global_load_dword v11, v[82:83], off offset:2048
	ds_read_b128 v[128:131], v12 offset:14336
	ds_read_b128 v[132:135], v12 offset:14352
	ds_read_b128 v[222:225], v12 offset:14368
	ds_read_b128 v[226:229], v12 offset:14384
	s_waitcnt vmcnt(26) lgkmcnt(0)
	v_mul_f32_e32 v6, v159, v129
	v_mul_f32_e32 v7, v19, v129
	v_fmac_f32_e32 v6, v158, v128
	v_fmac_f32_e32 v7, v18, v128
	v_fmac_f32_e32 v6, v160, v130
	v_fmac_f32_e32 v7, v20, v130
	v_fmac_f32_e32 v6, v161, v131
	v_fmac_f32_e32 v7, v21, v131
	v_add_f32_e32 v4, 0, v6
	v_add_f32_e32 v5, 0, v7
	v_mul_f32_e32 v6, v163, v133
	v_mul_f32_e32 v7, v23, v133
	v_fmac_f32_e32 v6, v162, v132
	v_fmac_f32_e32 v7, v22, v132
	v_fmac_f32_e32 v6, v164, v134
	v_fmac_f32_e32 v7, v24, v134
	v_fmac_f32_e32 v6, v165, v135
	v_fmac_f32_e32 v7, v25, v135
	v_add_f32_e32 v4, v4, v6
	v_add_f32_e32 v5, v5, v7
	v_mul_f32_e32 v6, v167, v223
	v_mul_f32_e32 v7, v27, v223
	v_fmac_f32_e32 v6, v166, v222
	v_fmac_f32_e32 v7, v26, v222
	v_fmac_f32_e32 v6, v168, v224
	v_fmac_f32_e32 v7, v28, v224
	v_fmac_f32_e32 v6, v169, v225
	v_fmac_f32_e32 v7, v29, v225
	v_add_f32_e32 v4, v4, v6
	v_add_f32_e32 v5, v5, v7
	v_mul_f32_e32 v6, v171, v227
	v_mul_f32_e32 v7, v35, v227
	v_fmac_f32_e32 v6, v170, v226
	v_fmac_f32_e32 v7, v34, v226
	v_fmac_f32_e32 v6, v172, v228
	v_fmac_f32_e32 v7, v36, v228
	v_fmac_f32_e32 v6, v173, v229
	v_fmac_f32_e32 v7, v37, v229
	v_add_f32_e32 v4, v4, v6
	v_add_f32_e32 v5, v5, v7
	ds_read_b128 v[128:131], v12 offset:14400
	ds_read_b128 v[132:135], v12 offset:14416
	ds_read_b128 v[222:225], v12 offset:14432
	ds_read_b128 v[226:229], v12 offset:14448
	s_waitcnt vmcnt(18) lgkmcnt(0)
; #define LAS __attribute__((address_space(3)))
; DI void tok0_mem(ldsp lds, const float* qm, const float* memb, const float* mnw, const float* Wkv, int hm, LAS float* out64, int tid, int wid, int lane) {
;     ...
;     for (int h2 = 0; h2 < 2; ++h2) {
;         const int j = tid + h2 * 512; const float* wr = Wkv + (size_t)j * 512 + hm * 64; float t = 0.f;
; #pragma unroll
;         for (int d4 = 0; d4 < 16; ++d4) { const float4 w4 = *(const float4*)(wr + d4 * 4); const f32x4 q4 = *(LAS f32x4*)(QS + d4 * 4); t += w4.x * q4[0] + w4.y * q4[1] + w4.z * q4[2] + w4.w * q4[3]; }
;         U[j] = t * mnw[j];
;     }
;     __syncthreads();
;     {
;         f32x4 u4[4];
; #pragma unroll
;         for (int q = 0; q < 4; ++q) u4[q] = *(LAS f32x4*)(U + q * 256 + lane * 4);
	v_mul_f32_e32 v6, v175, v129
	v_mul_f32_e32 v7, v39, v129
	v_fmac_f32_e32 v6, v174, v128
	v_fmac_f32_e32 v7, v38, v128
	v_fmac_f32_e32 v6, v176, v130
	v_fmac_f32_e32 v7, v40, v130
	v_fmac_f32_e32 v6, v177, v131
	v_fmac_f32_e32 v7, v41, v131
	v_add_f32_e32 v4, v4, v6
	v_add_f32_e32 v5, v5, v7
	v_mul_f32_e32 v6, v179, v133
	v_mul_f32_e32 v7, v43, v133
	v_fmac_f32_e32 v6, v178, v132
	v_fmac_f32_e32 v7, v42, v132
	v_fmac_f32_e32 v6, v180, v134
	v_fmac_f32_e32 v7, v44, v134
	v_fmac_f32_e32 v6, v181, v135
	v_fmac_f32_e32 v7, v45, v135
	v_add_f32_e32 v4, v4, v6
	v_add_f32_e32 v5, v5, v7
	v_mul_f32_e32 v6, v183, v223
	v_mul_f32_e32 v7, v47, v223
	v_fmac_f32_e32 v6, v182, v222
	v_fmac_f32_e32 v7, v46, v222
	v_fmac_f32_e32 v6, v184, v224
	v_fmac_f32_e32 v7, v48, v224
	v_fmac_f32_e32 v6, v185, v225
	v_fmac_f32_e32 v7, v49, v225
	v_add_f32_e32 v4, v4, v6
	v_add_f32_e32 v5, v5, v7
	v_mul_f32_e32 v6, v187, v227
	v_mul_f32_e32 v7, v51, v227
	v_fmac_f32_e32 v6, v186, v226
	v_fmac_f32_e32 v7, v50, v226
	v_fmac_f32_e32 v6, v188, v228
	v_fmac_f32_e32 v7, v52, v228
	v_fmac_f32_e32 v6, v189, v229
	v_fmac_f32_e32 v7, v53, v229
	v_add_f32_e32 v4, v4, v6
	v_add_f32_e32 v5, v5, v7
	ds_read_b128 v[128:131], v12 offset:14464
	ds_read_b128 v[132:135], v12 offset:14480
	ds_read_b128 v[222:225], v12 offset:14496
	ds_read_b128 v[226:229], v12 offset:14512
	s_waitcnt vmcnt(10) lgkmcnt(0)
	v_mul_f32_e32 v6, v191, v129
	v_mul_f32_e32 v7, v55, v129
	v_fmac_f32_e32 v6, v190, v128
	v_fmac_f32_e32 v7, v54, v128
	v_fmac_f32_e32 v6, v192, v130
	v_fmac_f32_e32 v7, v56, v130
	v_fmac_f32_e32 v6, v193, v131
	v_fmac_f32_e32 v7, v57, v131
	v_add_f32_e32 v4, v4, v6
	v_add_f32_e32 v5, v5, v7
	v_mul_f32_e32 v6, v195, v133
	v_mul_f32_e32 v7, v59, v133
	v_fmac_f32_e32 v6, v194, v132
	v_fmac_f32_e32 v7, v58, v132
	v_fmac_f32_e32 v6, v196, v134
	v_fmac_f32_e32 v7, v60, v134
	v_fmac_f32_e32 v6, v197, v135
	v_fmac_f32_e32 v7, v61, v135
	v_add_f32_e32 v4, v4, v6
	v_add_f32_e32 v5, v5, v7
	v_mul_f32_e32 v6, v199, v223
	v_mul_f32_e32 v7, v63, v223
	v_fmac_f32_e32 v6, v198, v222
	v_fmac_f32_e32 v7, v62, v222
	v_fmac_f32_e32 v6, v200, v224
	v_fmac_f32_e32 v7, v64, v224
	v_fmac_f32_e32 v6, v201, v225
	v_fmac_f32_e32 v7, v65, v225
	v_add_f32_e32 v4, v4, v6
	v_add_f32_e32 v5, v5, v7
	v_mul_f32_e32 v6, v203, v227
	v_mul_f32_e32 v7, v67, v227
	v_fmac_f32_e32 v6, v202, v226
	v_fmac_f32_e32 v7, v66, v226
	v_fmac_f32_e32 v6, v204, v228
	v_fmac_f32_e32 v7, v68, v228
	v_fmac_f32_e32 v6, v205, v229
	v_fmac_f32_e32 v7, v69, v229
	v_add_f32_e32 v4, v4, v6
	v_add_f32_e32 v5, v5, v7
	ds_read_b128 v[128:131], v12 offset:14528
	ds_read_b128 v[132:135], v12 offset:14544
	ds_read_b128 v[222:225], v12 offset:14560
	ds_read_b128 v[226:229], v12 offset:14576
	s_waitcnt vmcnt(2) lgkmcnt(0)
	v_mul_f32_e32 v6, v207, v129
	v_mul_f32_e32 v7, v71, v129
	v_fmac_f32_e32 v6, v206, v128
	v_fmac_f32_e32 v7, v70, v128
	v_fmac_f32_e32 v6, v208, v130
	v_fmac_f32_e32 v7, v72, v130
	v_fmac_f32_e32 v6, v209, v131
	v_fmac_f32_e32 v7, v73, v131
	v_add_f32_e32 v4, v4, v6
	v_add_f32_e32 v5, v5, v7
	v_mul_f32_e32 v6, v211, v133
	v_mul_f32_e32 v7, v75, v133
	v_fmac_f32_e32 v6, v210, v132
	v_fmac_f32_e32 v7, v74, v132
	v_fmac_f32_e32 v6, v212, v134
	v_fmac_f32_e32 v7, v76, v134
	v_fmac_f32_e32 v6, v213, v135
	v_fmac_f32_e32 v7, v77, v135
	v_add_f32_e32 v4, v4, v6
	v_add_f32_e32 v5, v5, v7
	v_mul_f32_e32 v6, v215, v223
	v_mul_f32_e32 v7, v121, v223
	v_fmac_f32_e32 v6, v214, v222
	v_fmac_f32_e32 v7, v120, v222
	v_fmac_f32_e32 v6, v216, v224
	v_fmac_f32_e32 v7, v122, v224
	v_fmac_f32_e32 v6, v217, v225
	v_fmac_f32_e32 v7, v123, v225
	v_add_f32_e32 v4, v4, v6
	v_add_f32_e32 v5, v5, v7
	v_mul_f32_e32 v6, v219, v227
	v_mul_f32_e32 v7, v125, v227
	v_fmac_f32_e32 v6, v218, v226
	v_fmac_f32_e32 v7, v124, v226
	v_fmac_f32_e32 v6, v220, v228
	v_fmac_f32_e32 v7, v126, v228
	v_fmac_f32_e32 v6, v221, v229
	v_fmac_f32_e32 v7, v127, v229
	v_add_f32_e32 v4, v4, v6
	v_add_f32_e32 v5, v5, v7
	s_waitcnt vmcnt(1)
	v_mul_f32_e32 v10, v10, v4
	ds_write_b32 v13, v10
	s_waitcnt vmcnt(0)
	v_mul_f32_e32 v11, v11, v5
	ds_write_b32 v13, v11 offset:2048
	s_waitcnt lgkmcnt(0)
	s_barrier
	ds_read_b128 v[0:3], v94
	ds_read_b128 v[4:7], v94 offset:1024
	ds_read_b128 v[8:11], v94 offset:2048
	ds_read_b128 v[14:17], v94 offset:3072
	s_branch .Lp2_entry_s5

; #define LAS __attribute__((address_space(3)))
; DI void tok0_mem(ldsp lds, const float* qm, const float* memb, const float* mnw, const float* Wkv, int hm, LAS float* out64, int tid, int wid, int lane) {
;     ...
;     for (int h2 = 0; h2 < 2; ++h2) {
;         const int j = tid + h2 * 512; const float* wr = Wkv + (size_t)j * 512 + hm * 64; float t = 0.f;
; #pragma unroll
;         for (int d4 = 0; d4 < 16; ++d4) { const float4 w4 = *(const float4*)(wr + d4 * 4); const f32x4 q4 = *(LAS f32x4*)(QS + d4 * 4); t += w4.x * q4[0] + w4.y * q4[1] + w4.z * q4[2] + w4.w * q4[3]; }
;         U[j] = t * mnw[j];
;     }
;     __syncthreads();
;     {
;         f32x4 u4[4];
; #pragma unroll
;         for (int q = 0; q < 4; ++q) u4[q] = *(LAS f32x4*)(U + q * 256 + lane * 4);
.LBB0_832:
	s_or_b64 exec, exec, s[22:23]
	v_readlane_b32 s52, v254, 15
	s_lshl_b64 s[26:27], s[46:47], 20
	s_lshl_b32 s50, s51, 2
	v_readlane_b32 s60, v254, 23
	v_readlane_b32 s61, v254, 24
	s_add_u32 s30, s60, s50
	s_addc_u32 s31, s61, 0
	v_lshlrev_b64 v[2:3], 11, v[0:1]
	v_lshl_add_u64 v[2:3], s[30:31], 0, v[2:3]
	s_waitcnt lgkmcnt(0)
	s_barrier
	v_readlane_b32 s56, v254, 19
	v_readlane_b32 s57, v254, 20
	v_lshl_add_u64 v[94:95], v[84:85], 0, s[26:27]
	s_mov_b32 s0, -4
	v_lshl_add_u64 v[92:93], v[0:1], 2, s[56:57]
	v_readlane_b32 s53, v254, 16
	v_readlane_b32 s54, v254, 17
	v_readlane_b32 s55, v254, 18
	v_readlane_b32 s58, v254, 21
	v_readlane_b32 s59, v254, 22
	v_readlane_b32 s62, v254, 25
	v_readlane_b32 s63, v254, 26
	v_readlane_b32 s64, v254, 27
	v_readlane_b32 s65, v254, 28
	v_readlane_b32 s66, v254, 29
	v_readlane_b32 s67, v254, 30
	v_lshl_add_u64 v[246:247], s[30:31], 0, v[78:79]
	s_mov_b32 s30, s34
	global_load_dwordx4 v[158:161], v[2:3], off
	global_load_dwordx4 v[18:21], v[246:247], off
	global_load_dwordx4 v[162:165], v[2:3], off offset:16
	global_load_dwordx4 v[22:25], v[246:247], off offset:16
	global_load_dwordx4 v[166:169], v[2:3], off offset:32
	global_load_dwordx4 v[26:29], v[246:247], off offset:32
	global_load_dwordx4 v[170:173], v[2:3], off offset:48
	global_load_dwordx4 v[34:37], v[246:247], off offset:48
	global_load_dwordx4 v[174:177], v[2:3], off offset:64
	global_load_dwordx4 v[38:41], v[246:247], off offset:64
	global_load_dwordx4 v[178:181], v[2:3], off offset:80
	global_load_dwordx4 v[42:45], v[246:247], off offset:80
	global_load_dwordx4 v[182:185], v[2:3], off offset:96
	global_load_dwordx4 v[46:49], v[246:247], off offset:96
	global_load_dwordx4 v[186:189], v[2:3], off offset:112
	global_load_dwordx4 v[50:53], v[246:247], off offset:112
	global_load_dwordx4 v[190:193], v[2:3], off offset:128
	global_load_dwordx4 v[54:57], v[246:247], off offset:128
	global_load_dwordx4 v[194:197], v[2:3], off offset:144
	global_load_dwordx4 v[58:61], v[246:247], off offset:144
	global_load_dwordx4 v[198:201], v[2:3], off offset:160
	global_load_dwordx4 v[62:65], v[246:247], off offset:160
	global_load_dwordx4 v[202:205], v[2:3], off offset:176
	global_load_dwordx4 v[66:69], v[246:247], off offset:176
	global_load_dwordx4 v[206:209], v[2:3], off offset:192
	global_load_dwordx4 v[70:73], v[246:247], off offset:192
	global_load_dwordx4 v[210:213], v[2:3], off offset:208
	global_load_dwordx4 v[74:77], v[246:247], off offset:208
	global_load_dwordx4 v[214:217], v[2:3], off offset:224
	global_load_dwordx4 v[120:123], v[246:247], off offset:224
	global_load_dwordx4 v[218:221], v[2:3], off offset:240
	global_load_dwordx4 v[124:127], v[246:247], off offset:240
	global_load_dword v10, v[92:93], off
	global_load_dword v11, v[80:81], off offset:2048
	ds_read_b128 v[128:131], v12 offset:14336
	ds_read_b128 v[132:135], v12 offset:14352
	ds_read_b128 v[222:225], v12 offset:14368
	ds_read_b128 v[226:229], v12 offset:14384
	s_waitcnt vmcnt(26) lgkmcnt(0)
	v_mul_f32_e32 v6, v159, v129
	v_mul_f32_e32 v7, v19, v129
	v_fmac_f32_e32 v6, v158, v128
	v_fmac_f32_e32 v7, v18, v128
	v_fmac_f32_e32 v6, v160, v130
	v_fmac_f32_e32 v7, v20, v130
	v_fmac_f32_e32 v6, v161, v131
	v_fmac_f32_e32 v7, v21, v131
	v_add_f32_e32 v4, 0, v6
	v_add_f32_e32 v5, 0, v7
	v_mul_f32_e32 v6, v163, v133
	v_mul_f32_e32 v7, v23, v133
	v_fmac_f32_e32 v6, v162, v132
	v_fmac_f32_e32 v7, v22, v132
	v_fmac_f32_e32 v6, v164, v134
	v_fmac_f32_e32 v7, v24, v134
	v_fmac_f32_e32 v6, v165, v135
	v_fmac_f32_e32 v7, v25, v135
	v_add_f32_e32 v4, v4, v6
	v_add_f32_e32 v5, v5, v7
	v_mul_f32_e32 v6, v167, v223
	v_mul_f32_e32 v7, v27, v223
	v_fmac_f32_e32 v6, v166, v222
	v_fmac_f32_e32 v7, v26, v222
	v_fmac_f32_e32 v6, v168, v224
	v_fmac_f32_e32 v7, v28, v224
	v_fmac_f32_e32 v6, v169, v225
	v_fmac_f32_e32 v7, v29, v225
	v_add_f32_e32 v4, v4, v6
	v_add_f32_e32 v5, v5, v7
	v_mul_f32_e32 v6, v171, v227
	v_mul_f32_e32 v7, v35, v227
	v_fmac_f32_e32 v6, v170, v226
	v_fmac_f32_e32 v7, v34, v226
	v_fmac_f32_e32 v6, v172, v228
	v_fmac_f32_e32 v7, v36, v228
	v_fmac_f32_e32 v6, v173, v229
	v_fmac_f32_e32 v7, v37, v229
	v_add_f32_e32 v4, v4, v6
	v_add_f32_e32 v5, v5, v7
	ds_read_b128 v[128:131], v12 offset:14400
	ds_read_b128 v[132:135], v12 offset:14416
	ds_read_b128 v[222:225], v12 offset:14432
	ds_read_b128 v[226:229], v12 offset:14448
	s_waitcnt vmcnt(18) lgkmcnt(0)
; #define LAS __attribute__((address_space(3)))
; DI void tok0_mem(ldsp lds, const float* qm, const float* memb, const float* mnw, const float* Wkv, int hm, LAS float* out64, int tid, int wid, int lane) {
;     ...
;     for (int h2 = 0; h2 < 2; ++h2) {
;         const int j = tid + h2 * 512; const float* wr = Wkv + (size_t)j * 512 + hm * 64; float t = 0.f;
; #pragma unroll
;         for (int d4 = 0; d4 < 16; ++d4) { const float4 w4 = *(const float4*)(wr + d4 * 4); const f32x4 q4 = *(LAS f32x4*)(QS + d4 * 4); t += w4.x * q4[0] + w4.y * q4[1] + w4.z * q4[2] + w4.w * q4[3]; }
;         U[j] = t * mnw[j];
;     }
;     __syncthreads();
;     {
;         f32x4 u4[4];
; #pragma unroll
;         for (int q = 0; q < 4; ++q) u4[q] = *(LAS f32x4*)(U + q * 256 + lane * 4);
	v_mul_f32_e32 v6, v175, v129
	v_mul_f32_e32 v7, v39, v129
	v_fmac_f32_e32 v6, v174, v128
	v_fmac_f32_e32 v7, v38, v128
	v_fmac_f32_e32 v6, v176, v130
	v_fmac_f32_e32 v7, v40, v130
	v_fmac_f32_e32 v6, v177, v131
	v_fmac_f32_e32 v7, v41, v131
	v_add_f32_e32 v4, v4, v6
	v_add_f32_e32 v5, v5, v7
	v_mul_f32_e32 v6, v179, v133
	v_mul_f32_e32 v7, v43, v133
	v_fmac_f32_e32 v6, v178, v132
	v_fmac_f32_e32 v7, v42, v132
	v_fmac_f32_e32 v6, v180, v134
	v_fmac_f32_e32 v7, v44, v134
	v_fmac_f32_e32 v6, v181, v135
	v_fmac_f32_e32 v7, v45, v135
	v_add_f32_e32 v4, v4, v6
	v_add_f32_e32 v5, v5, v7
	v_mul_f32_e32 v6, v183, v223
	v_mul_f32_e32 v7, v47, v223
	v_fmac_f32_e32 v6, v182, v222
	v_fmac_f32_e32 v7, v46, v222
	v_fmac_f32_e32 v6, v184, v224
	v_fmac_f32_e32 v7, v48, v224
	v_fmac_f32_e32 v6, v185, v225
	v_fmac_f32_e32 v7, v49, v225
	v_add_f32_e32 v4, v4, v6
	v_add_f32_e32 v5, v5, v7
	v_mul_f32_e32 v6, v187, v227
	v_mul_f32_e32 v7, v51, v227
	v_fmac_f32_e32 v6, v186, v226
	v_fmac_f32_e32 v7, v50, v226
	v_fmac_f32_e32 v6, v188, v228
	v_fmac_f32_e32 v7, v52, v228
	v_fmac_f32_e32 v6, v189, v229
	v_fmac_f32_e32 v7, v53, v229
	v_add_f32_e32 v4, v4, v6
	v_add_f32_e32 v5, v5, v7
	ds_read_b128 v[128:131], v12 offset:14464
	ds_read_b128 v[132:135], v12 offset:14480
	ds_read_b128 v[222:225], v12 offset:14496
	ds_read_b128 v[226:229], v12 offset:14512
	s_waitcnt vmcnt(10) lgkmcnt(0)
	v_mul_f32_e32 v6, v191, v129
	v_mul_f32_e32 v7, v55, v129
	v_fmac_f32_e32 v6, v190, v128
	v_fmac_f32_e32 v7, v54, v128
	v_fmac_f32_e32 v6, v192, v130
	v_fmac_f32_e32 v7, v56, v130
	v_fmac_f32_e32 v6, v193, v131
	v_fmac_f32_e32 v7, v57, v131
	v_add_f32_e32 v4, v4, v6
	v_add_f32_e32 v5, v5, v7
	v_mul_f32_e32 v6, v195, v133
	v_mul_f32_e32 v7, v59, v133
	v_fmac_f32_e32 v6, v194, v132
	v_fmac_f32_e32 v7, v58, v132
	v_fmac_f32_e32 v6, v196, v134
	v_fmac_f32_e32 v7, v60, v134
	v_fmac_f32_e32 v6, v197, v135
	v_fmac_f32_e32 v7, v61, v135
	v_add_f32_e32 v4, v4, v6
	v_add_f32_e32 v5, v5, v7
	v_mul_f32_e32 v6, v199, v223
	v_mul_f32_e32 v7, v63, v223
	v_fmac_f32_e32 v6, v198, v222
	v_fmac_f32_e32 v7, v62, v222
	v_fmac_f32_e32 v6, v200, v224
	v_fmac_f32_e32 v7, v64, v224
	v_fmac_f32_e32 v6, v201, v225
	v_fmac_f32_e32 v7, v65, v225
	v_add_f32_e32 v4, v4, v6
	v_add_f32_e32 v5, v5, v7
	v_mul_f32_e32 v6, v203, v227
	v_mul_f32_e32 v7, v67, v227
	v_fmac_f32_e32 v6, v202, v226
	v_fmac_f32_e32 v7, v66, v226
	v_fmac_f32_e32 v6, v204, v228
	v_fmac_f32_e32 v7, v68, v228
	v_fmac_f32_e32 v6, v205, v229
	v_fmac_f32_e32 v7, v69, v229
	v_add_f32_e32 v4, v4, v6
	v_add_f32_e32 v5, v5, v7
	ds_read_b128 v[128:131], v12 offset:14528
	ds_read_b128 v[132:135], v12 offset:14544
	ds_read_b128 v[222:225], v12 offset:14560
	ds_read_b128 v[226:229], v12 offset:14576
	s_waitcnt vmcnt(2) lgkmcnt(0)
	v_mul_f32_e32 v6, v207, v129
	v_mul_f32_e32 v7, v71, v129
	v_fmac_f32_e32 v6, v206, v128
	v_fmac_f32_e32 v7, v70, v128
	v_fmac_f32_e32 v6, v208, v130
	v_fmac_f32_e32 v7, v72, v130
	v_fmac_f32_e32 v6, v209, v131
	v_fmac_f32_e32 v7, v73, v131
	v_add_f32_e32 v4, v4, v6
	v_add_f32_e32 v5, v5, v7
	v_mul_f32_e32 v6, v211, v133
	v_mul_f32_e32 v7, v75, v133
	v_fmac_f32_e32 v6, v210, v132
	v_fmac_f32_e32 v7, v74, v132
	v_fmac_f32_e32 v6, v212, v134
	v_fmac_f32_e32 v7, v76, v134
	v_fmac_f32_e32 v6, v213, v135
	v_fmac_f32_e32 v7, v77, v135
	v_add_f32_e32 v4, v4, v6
	v_add_f32_e32 v5, v5, v7
	v_mul_f32_e32 v6, v215, v223
	v_mul_f32_e32 v7, v121, v223
	v_fmac_f32_e32 v6, v214, v222
	v_fmac_f32_e32 v7, v120, v222
	v_fmac_f32_e32 v6, v216, v224
	v_fmac_f32_e32 v7, v122, v224
	v_fmac_f32_e32 v6, v217, v225
	v_fmac_f32_e32 v7, v123, v225
	v_add_f32_e32 v4, v4, v6
	v_add_f32_e32 v5, v5, v7
	v_mul_f32_e32 v6, v219, v227
	v_mul_f32_e32 v7, v125, v227
	v_fmac_f32_e32 v6, v218, v226
	v_fmac_f32_e32 v7, v124, v226
	v_fmac_f32_e32 v6, v220, v228
	v_fmac_f32_e32 v7, v126, v228
	v_fmac_f32_e32 v6, v221, v229
	v_fmac_f32_e32 v7, v127, v229
	v_add_f32_e32 v4, v4, v6
	v_add_f32_e32 v5, v5, v7
	s_waitcnt vmcnt(1)
	v_mul_f32_e32 v10, v10, v4
	ds_write_b32 v13, v10
	s_waitcnt vmcnt(0)
	v_mul_f32_e32 v11, v11, v5
	ds_write_b32 v13, v11 offset:2048
	s_waitcnt lgkmcnt(0)
	s_barrier
	ds_read_b128 v[0:3], v96
	ds_read_b128 v[4:7], v96 offset:1024
	ds_read_b128 v[8:11], v96 offset:2048
	ds_read_b128 v[14:17], v96 offset:3072
	s_branch .Lp2_entry_s2
